# group-local syncs skip the L2 write-back when a run-time XCC-id check shows the 32 workgroups of the group share one XCD (else unchanged)
# speedup vs baseline: 1.0276x; 1.0044x over previous
; __device__ __forceinline__ CArgs* get_args() { CArgs* p = (CArgs*)__builtin_amdgcn_kernarg_segment_ptr(); asm volatile("" : "+s"(p)); return p; }
; #define GRID_SYNC() do { asm volatile("s_waitcnt vmcnt(0) lgkmcnt(0)" ::: "memory"); grid.sync(); \
;     asm volatile("buffer_inv sc1\n\ts_waitcnt vmcnt(0) lgkmcnt(0)" ::: "memory"); } while (0)
; __global__ void __launch_bounds__(512, 2) hymba_fwd(Args A_unused) {
;     ...
;     unsigned nsync = 0;
;     ...
;     { PHASE_IDS(); if (blk == 0 && tid == 0) __hip_atomic_store((unsigned*)(get_args()->ws + WS_CTL), 0u, __ATOMIC_RELAXED, __HIP_MEMORY_SCOPE_AGENT);
;       prologue(lds, wave, lane, gw, NGW); }
;     GRID_SYNC();
; #pragma nounroll
;     for (int l = 0; l < DEPTH; ++l) {
.LBB0_346:
	s_or_b64 exec, exec, s[0:1]
	s_mov_b32 s0, 0
	s_mov_b32 s73, 0
	v_writelane_b32 v254, s0, 0
	v_writelane_b32 v254, s0, 1
	s_mov_b32 s1, 1
	v_writelane_b32 v254, s1, 61
	s_mov_b64 s[0:1], 0x80
	v_writelane_b32 v254, s0, 2
	s_barrier
	s_nop 0
	v_writelane_b32 v254, s1, 3
	s_mov_b32 s0, s73
	v_writelane_b32 v254, s0, 4
	buffer_inv sc1
	s_waitcnt vmcnt(0) lgkmcnt(0)
	s_cmp_lt_u32 s24, 64
	s_mov_b32 s74, s73
	v_writelane_b32 v254, s1, 5
	v_writelane_b32 v254, s68, 6
	s_mov_b32 s75, s73
	v_mbcnt_hi_u32_b32 v170, -1, v166
	v_writelane_b32 v254, s69, 7
	v_writelane_b32 v254, s67, 8
	v_writelane_b32 v254, s76, 9
	s_cselect_b64 s[92:93], -1, 0
	s_mov_b32 s72, s73
	v_mov_b64_e32 v[226:227], s[74:75]
	v_and_b32_e32 v177, 64, v170
	v_writelane_b32 v254, s77, 10
	s_mov_b64 s[70:71], 0x80
	s_mov_b64 s[80:81], 0x2aa00000
	s_mov_b64 s[82:83], 0x2a200000
	s_mov_b64 s[86:87], 0
	s_movk_i32 s84, 0x79
	v_mov_b32_e32 v145, 0
	v_mov_b32_e32 v167, 0x358637bd
	s_mov_b32 s33, 0x800000
	s_mov_b64 s[94:95], 0x80000
	s_movk_i32 s78, 0x200
	s_mov_b64 s[96:97], 0x1ba00000
	s_movk_i32 s79, 0x1e00
	v_mov_b32_e32 v168, 0xb9500d01
	v_mov_b32_e32 v169, 0xbab60b61
	s_movk_i32 s85, 0x1ff
	v_mov_b64_e32 v[224:225], s[72:73]
	s_mov_b32 s74, 0xf149f2ca
	v_mov_b32_e32 v173, 0x1000
	v_mov_b32_e32 v174, 0x2000
	v_mov_b32_e32 v175, 0x4000
	v_mov_b32_e32 v176, 0x8000
	s_movk_i32 s75, 0x3fe
	s_movk_i32 s90, 0x2c00
	v_xor_b32_e32 v172, 1, v170
	v_add_u32_e32 v171, 64, v177
	v_mov_b32_e32 v178, 1
	v_mov_b32_e32 v179, 0x7f800000
	v_mov_b32_e32 v180, 0x1e00
	v_mov_b32_e32 v181, 0x3ff
	v_mov_b32_e32 v182, 0xf149f2ca
	v_mov_b32_e32 v183, 0x80
	v_mov_b32_e32 v184, 0x100
	v_mov_b32_e32 v185, 0x200
	v_mov_b32_e32 v186, 0x400
	v_mov_b32_e32 v187, 0x800
	v_mov_b64_e32 v[146:147], 0x200
	v_mov_b64_e32 v[148:149], 0x1ff
	v_writelane_b32 v254, s92, 11
	s_nop 1
	v_writelane_b32 v254, s93, 12
	s_branch .LBB0_348

.LBB0_798:
	s_waitcnt vmcnt(0) lgkmcnt(0)
	s_waitcnt vmcnt(0)
	s_barrier
	v_mbcnt_lo_u32_b32 v0, -1, 0
	v_mbcnt_hi_u32_b32 v0, -1, v0
	s_nop 0
	v_cmp_eq_u32_e32 vcc, 0, v0
	s_and_b64 s[2:3], s[92:93], vcc
	s_and_saveexec_b64 s[0:1], s[2:3]
	s_cbranch_execz .LBB0_812
	s_mov_b64 s[2:3], s[68:69]
	s_load_dwordx2 s[2:3], s[2:3], 0xd8
	s_mov_b64 s[4:5], exec
	buffer_wbl2 sc1
	s_waitcnt lgkmcnt(0)
	s_waitcnt vmcnt(0)
	s_getreg_b32 s6, hwreg(HW_REG_XCC_ID, 0, 4)
	s_lshl_b32 s7, s76, 2
	v_mov_b32_e32 v1, s6
	v_mov_b32_e32 v2, s7
	global_store_dword v2, v1, s[2:3] offset:3072 sc1
	s_waitcnt vmcnt(0)
	v_mbcnt_lo_u32_b32 v0, s4, 0
	v_mbcnt_hi_u32_b32 v0, s5, v0
	v_cmp_eq_u32_e32 vcc, 0, v0
	s_and_saveexec_b64 s[6:7], vcc
	s_cbranch_execz .LBB0_801
	s_bcnt1_i32_b64 s4, s[4:5]
	v_mov_b32_e32 v0, s4
	s_and_b32 s4, s76, 7
	s_lshl_b32 s4, s4, 6
	s_add_i32 s4, s4, 0x400
	s_add_u32 s4, s2, s4
	s_addc_u32 s5, s3, 0
	global_atomic_add v145, v0, s[4:5]

.Lsyncinv_0:
	buffer_inv sc1
	s_waitcnt vmcnt(0)
	s_mov_b64 s[6:7], exec
	s_mov_b32 exec_lo, -1
	s_mov_b32 exec_hi, 1
	v_mbcnt_lo_u32_b32 v1, -1, 0
	v_mbcnt_hi_u32_b32 v1, -1, v1
	s_and_b32 s4, s76, 7
	s_lshl_b32 s4, s4, 2
	s_xor_b32 s5, s76, 1
	s_lshl_b32 s5, s5, 2
	v_cmp_eq_u32_e32 vcc, 32, v1
	v_lshl_add_u32 v1, v1, 5, s4
	v_mov_b32_e32 v2, s5
	v_cndmask_b32_e32 v1, v1, v2, vcc
	global_load_dword v2, v1, s[2:3] offset:3072 sc1
	s_getreg_b32 s4, hwreg(HW_REG_XCC_ID, 0, 4)
	s_waitcnt vmcnt(0)
	v_cmp_ne_u32_e32 vcc, s4, v2
	s_not_b32 s5, vcc_hi
	s_and_b32 s5, s5, 1
	s_or_b32 s5, s5, vcc_lo
	s_cmp_lg_u32 s5, 0
	s_cselect_b32 s4, 1, 0
	v_writelane_b32 v254, s4, 61
	s_mov_b64 exec, s[6:7]

.LBB0_1322:
	s_waitcnt vmcnt(0) lgkmcnt(0)
	s_barrier
	v_mbcnt_lo_u32_b32 v0, -1, 0
	v_mbcnt_hi_u32_b32 v0, -1, v0
	s_nop 0
	v_cmp_eq_u32_e32 vcc, 0, v0
	s_and_b64 s[2:3], s[92:93], vcc
	s_and_saveexec_b64 s[0:1], s[2:3]
	v_readlane_b32 s12, v254, 15
	v_readlane_b32 s13, v254, 16
	s_cbranch_execz .LBB0_1336
	s_mov_b64 s[2:3], s[68:69]
	s_load_dwordx2 s[2:3], s[2:3], 0xd8
	s_mov_b64 s[4:5], exec
	v_readlane_b32 s6, v254, 61
	s_cmp_eq_u32 s6, 0
	s_cbranch_scc1 .Lnowb_4
	buffer_wbl2 sc1
.Lnowb_4:
	s_waitcnt vmcnt(0) lgkmcnt(0)
	s_waitcnt vmcnt(0)
	v_mbcnt_lo_u32_b32 v0, s4, 0
	v_mbcnt_hi_u32_b32 v0, s5, v0
	v_cmp_eq_u32_e32 vcc, 0, v0
	s_and_saveexec_b64 s[6:7], vcc
	s_cbranch_execz .LBB0_1325
	s_bcnt1_i32_b64 s4, s[4:5]
	v_mov_b32_e32 v0, s4
	s_and_b32 s4, s76, 7
	s_lshl_b32 s4, s4, 6
	s_add_i32 s4, s4, 0x400
	s_add_u32 s4, s2, s4
	s_addc_u32 s5, s3, 0
	global_atomic_add v145, v0, s[4:5]

.LBB0_1378:
	s_waitcnt vmcnt(0) lgkmcnt(0)
	s_waitcnt lgkmcnt(0)
	s_barrier
	v_mbcnt_lo_u32_b32 v0, -1, 0
	v_mbcnt_hi_u32_b32 v0, -1, v0
	s_nop 0
	v_cmp_eq_u32_e32 vcc, 0, v0
	s_and_b64 s[2:3], s[92:93], vcc
	s_and_saveexec_b64 s[0:1], s[2:3]
	s_cbranch_execz .LBB0_1392
	s_mov_b64 s[2:3], s[68:69]
	s_load_dwordx2 s[2:3], s[2:3], 0xd8
	s_mov_b64 s[4:5], exec
	v_readlane_b32 s6, v254, 61
	s_cmp_eq_u32 s6, 0
	s_cbranch_scc1 .Lnowb_5
	buffer_wbl2 sc1

.LBB0_1450:
	s_waitcnt vmcnt(0) lgkmcnt(0)
	s_waitcnt vmcnt(0)
	s_barrier
	v_mbcnt_lo_u32_b32 v0, -1, 0
	v_mbcnt_hi_u32_b32 v0, -1, v0
	s_nop 0
	v_cmp_eq_u32_e32 vcc, 0, v0
	s_and_b64 s[2:3], s[92:93], vcc
	s_and_saveexec_b64 s[0:1], s[2:3]
	s_cbranch_execz .LBB0_1464
	s_mov_b64 s[2:3], s[68:69]
	s_load_dwordx2 s[2:3], s[2:3], 0xd8
	s_mov_b64 s[4:5], exec
	v_readlane_b32 s6, v254, 61
	s_cmp_eq_u32 s6, 0
	s_cbranch_scc1 .Lnowb_6
	buffer_wbl2 sc1
.Lnowb_6:
	s_waitcnt lgkmcnt(0)
	s_waitcnt vmcnt(0)
	v_mbcnt_lo_u32_b32 v0, s4, 0
	v_mbcnt_hi_u32_b32 v0, s5, v0
	v_cmp_eq_u32_e32 vcc, 0, v0
	s_and_saveexec_b64 s[6:7], vcc
	s_cbranch_execz .LBB0_1453
	s_bcnt1_i32_b64 s4, s[4:5]
	v_mov_b32_e32 v0, s4
	s_and_b32 s4, s76, 7
	s_lshl_b32 s4, s4, 6
	s_add_i32 s4, s4, 0x400
	s_add_u32 s4, s2, s4
	s_addc_u32 s5, s3, 0
	global_atomic_add v145, v0, s[4:5]

; __global__ void __launch_bounds__(512, 2) hymba_fwd(Args A_unused) {
;     ...
;         FAST_SYNC();
.LBB0_1510:
	s_waitcnt vmcnt(0) lgkmcnt(0)
	s_waitcnt lgkmcnt(0)
	s_barrier
	v_readlane_b32 s0, v254, 1
	v_mbcnt_lo_u32_b32 v0, -1, 0
	v_mbcnt_hi_u32_b32 v0, -1, v0
	s_add_i32 s0, s0, 7
	v_cmp_eq_u32_e32 vcc, 0, v0
	s_and_b64 s[2:3], s[92:93], vcc
	v_writelane_b32 v254, s0, 1
	s_and_saveexec_b64 s[0:1], s[2:3]
	s_cbranch_execz .LBB0_347
	s_mov_b64 s[2:3], s[68:69]
	s_load_dwordx2 s[2:3], s[2:3], 0xd8
	s_mov_b64 s[4:5], exec
	v_readlane_b32 s6, v254, 61
	v_readlane_b32 s7, v254, 1
	s_cmp_eq_u32 s7, 28
	s_cselect_b32 s6, 1, s6
	s_cmp_eq_u32 s6, 0
	s_cbranch_scc1 .Lnowb_7
	buffer_wbl2 sc1
